# conv filter staging: all 8 shifted copies of a position built in one pass (8 LDS reads in flight, one wait) instead of 72 dependent read-wait-write round trips per unit
# speedup vs baseline: 1.0111x; 1.0023x over previous
.LBB0_965:
	s_or_b64 exec, exec, s[8:9]
	s_lshl_b32 s2, s20, 1
	s_or_b32 s0, s20, 0x88
	v_cmp_gt_i32_e64 s[36:37], s0, v42
	v_add_u32_e32 v0, s2, v49
	v_add_u32_e32 v1, s20, v50
	s_mov_b32 s1, 0
	v_mov_b32_e32 v2, v51
	s_waitcnt lgkmcnt(0)
	s_barrier
	s_and_saveexec_b64 s[8:9], s[36:37]
	s_cbranch_execz .Lconv_copy_done_0
	v_add_u32_e32 v5, -14, v0
	v_mov_b32_e32 v3, v2
	v_mov_b32_e32 v4, v1
	v_mov_b32_e32 v6, v42
	s_mov_b64 s[100:101], 0
.Lconv_copy_loop_0:
	ds_read_u16 v80, v5 offset:14
	ds_read_u16 v81, v5 offset:12
	ds_read_u16 v82, v5 offset:10
	ds_read_u16 v83, v5 offset:8
	ds_read_u16 v84, v5 offset:6
	ds_read_u16 v85, v5 offset:4
	ds_read_u16 v86, v5 offset:2
	ds_read_u16 v87, v5
	s_waitcnt lgkmcnt(0)
	v_cmp_gt_u32_e64 s[38:39], s20, v4
	s_nop 1
	v_cndmask_b32_e64 v80, 0, v80, s[38:39]
	ds_write_b16 v3, v80
	v_add_u32_e32 v7, -1, v4
	v_cmp_gt_u32_e64 s[38:39], s20, v7
	s_nop 1
	v_cndmask_b32_e64 v81, 0, v81, s[38:39]
	ds_write_b16 v3, v81 offset:8512
	v_add_u32_e32 v7, -2, v4
	v_cmp_gt_u32_e64 s[38:39], s20, v7
	s_nop 1
	v_cndmask_b32_e64 v82, 0, v82, s[38:39]
	ds_write_b16 v3, v82 offset:17024
	v_add_u32_e32 v7, -3, v4
	v_cmp_gt_u32_e64 s[38:39], s20, v7
	s_nop 1
	v_cndmask_b32_e64 v83, 0, v83, s[38:39]
	ds_write_b16 v3, v83 offset:25536
	v_add_u32_e32 v7, -4, v4
	v_cmp_gt_u32_e64 s[38:39], s20, v7
	s_nop 1
	v_cndmask_b32_e64 v84, 0, v84, s[38:39]
	ds_write_b16 v3, v84 offset:34048
	v_add_u32_e32 v7, -5, v4
	v_cmp_gt_u32_e64 s[38:39], s20, v7
	s_nop 1
	v_cndmask_b32_e64 v85, 0, v85, s[38:39]
	ds_write_b16 v3, v85 offset:42560
	v_add_u32_e32 v7, -6, v4
	v_cmp_gt_u32_e64 s[38:39], s20, v7
	s_nop 1
	v_cndmask_b32_e64 v86, 0, v86, s[38:39]
	ds_write_b16 v3, v86 offset:51072
	v_add_u32_e32 v7, -7, v4
	v_cmp_gt_u32_e64 s[38:39], s20, v7
	s_nop 1
	v_cndmask_b32_e64 v87, 0, v87, s[38:39]
	ds_write_b16 v3, v87 offset:59584
	v_add_u32_e32 v6, 0x200, v6
	v_cmp_le_i32_e64 s[38:39], s0, v6
	v_add_u32_e32 v5, 0xfffffc00, v5
	v_add_u32_e32 v4, 0xfffffe00, v4
	v_add_u32_e32 v3, 0x400, v3
	s_or_b64 s[100:101], s[38:39], s[100:101]
	s_andn2_b64 exec, exec, s[100:101]
	s_cbranch_execnz .Lconv_copy_loop_0
.Lconv_copy_done_0:
	s_or_b64 exec, exec, s[8:9]
.LBB0_972:
	s_and_b64 s[0:1], vcc, exec
	s_cselect_b32 s84, 32, 8
	s_cselect_b32 s0, 5, 9
	s_lshl_b32 s1, s84, s0
	s_lshl_b32 s6, s48, 2
	s_add_u32 s14, s60, s6
	s_addc_u32 s15, s61, 0
	s_add_u32 s8, s65, s6
	s_addc_u32 s9, s76, 0
	v_cmp_le_i32_e64 s[36:37], s1, v42
	s_waitcnt lgkmcnt(0)
	s_barrier
	s_and_saveexec_b64 s[6:7], s[36:37]
	s_xor_b64 s[6:7], exec, s[6:7]
	s_and_b64 s[10:11], vcc, exec
	s_cselect_b32 s12, 8, 12
	s_or_saveexec_b64 s[10:11], s[6:7]
	s_or_b32 s79, s2, 16
	v_mov_b32_e32 v0, s12
	s_xor_b64 exec, exec, s[10:11]
	s_cbranch_execz .LBB0_982
	global_load_dword v6, v165, s[14:15]
	global_load_dword v7, v191, s[14:15] offset:2048
	global_load_dword v8, v165, s[8:9]
	global_load_dword v9, v192, s[14:15]
	s_lshl_b32 s6, -1, s0
	s_add_i32 s2, s20, -8
	s_not_b32 s22, s6
	s_and_b64 s[6:7], vcc, exec
	s_cselect_b32 s21, 8, 12
	s_lshl_b32 s6, s48, s21
	s_lshl_b32 s6, s6, 1
	s_add_u32 s12, s4, s6
	s_addc_u32 s13, s5, 0
	s_mov_b64 s[16:17], 0
	v_mov_b32_e32 v10, v42
	s_branch .LBB0_977

.LBB0_1083:
	s_or_b64 exec, exec, s[10:11]
	s_lshl_b32 s0, s20, 1
	s_or_b32 s1, s20, 0x88
	v_cmp_gt_i32_e64 s[34:35], s1, v44
	v_add_u32_e32 v0, s0, v51
	v_add_u32_e32 v1, s20, v52
	s_mov_b32 s14, 0
	v_mov_b32_e32 v2, v53
	s_waitcnt lgkmcnt(0)
	s_barrier
	s_and_saveexec_b64 s[10:11], s[34:35]
	s_cbranch_execz .Lconv_copy_done_1
	v_add_u32_e32 v5, -14, v0
	v_mov_b32_e32 v3, v2
	v_mov_b32_e32 v4, v1
	v_mov_b32_e32 v6, v44
	s_mov_b64 s[100:101], 0
.Lconv_copy_loop_1:
	ds_read_u16 v80, v5 offset:14
	ds_read_u16 v81, v5 offset:12
	ds_read_u16 v82, v5 offset:10
	ds_read_u16 v83, v5 offset:8
	ds_read_u16 v84, v5 offset:6
	ds_read_u16 v85, v5 offset:4
	ds_read_u16 v86, v5 offset:2
	ds_read_u16 v87, v5
	s_waitcnt lgkmcnt(0)
	v_cmp_gt_u32_e64 s[36:37], s20, v4
	s_nop 1
	v_cndmask_b32_e64 v80, 0, v80, s[36:37]
	ds_write_b16 v3, v80
	v_add_u32_e32 v7, -1, v4
	v_cmp_gt_u32_e64 s[36:37], s20, v7
	s_nop 1
	v_cndmask_b32_e64 v81, 0, v81, s[36:37]
	ds_write_b16 v3, v81 offset:8512
	v_add_u32_e32 v7, -2, v4
	v_cmp_gt_u32_e64 s[36:37], s20, v7
	s_nop 1
	v_cndmask_b32_e64 v82, 0, v82, s[36:37]
	ds_write_b16 v3, v82 offset:17024
	v_add_u32_e32 v7, -3, v4
	v_cmp_gt_u32_e64 s[36:37], s20, v7
	s_nop 1
	v_cndmask_b32_e64 v83, 0, v83, s[36:37]
	ds_write_b16 v3, v83 offset:25536
	v_add_u32_e32 v7, -4, v4
	v_cmp_gt_u32_e64 s[36:37], s20, v7
	s_nop 1
	v_cndmask_b32_e64 v84, 0, v84, s[36:37]
	ds_write_b16 v3, v84 offset:34048
	v_add_u32_e32 v7, -5, v4
	v_cmp_gt_u32_e64 s[36:37], s20, v7
	s_nop 1
	v_cndmask_b32_e64 v85, 0, v85, s[36:37]
	ds_write_b16 v3, v85 offset:42560
	v_add_u32_e32 v7, -6, v4
	v_cmp_gt_u32_e64 s[36:37], s20, v7
	s_nop 1
	v_cndmask_b32_e64 v86, 0, v86, s[36:37]
	ds_write_b16 v3, v86 offset:51072
	v_add_u32_e32 v7, -7, v4
	v_cmp_gt_u32_e64 s[36:37], s20, v7
	s_nop 1
	v_cndmask_b32_e64 v87, 0, v87, s[36:37]
	ds_write_b16 v3, v87 offset:59584
	v_add_u32_e32 v6, 0x200, v6
	v_cmp_le_i32_e64 s[36:37], s1, v6
	v_add_u32_e32 v5, 0xfffffc00, v5
	v_add_u32_e32 v4, 0xfffffe00, v4
	v_add_u32_e32 v3, 0x400, v3
	s_or_b64 s[100:101], s[36:37], s[100:101]
	s_andn2_b64 exec, exec, s[100:101]
	s_cbranch_execnz .Lconv_copy_loop_1
.Lconv_copy_done_1:
	s_or_b64 exec, exec, s[10:11]
.LBB0_1090:
	s_and_b64 s[6:7], vcc, exec
	s_cselect_b32 s79, 32, 8
	s_cselect_b32 s1, 5, 9
	s_lshl_b32 s21, s79, s1
	v_cmp_le_i32_e64 s[34:35], s21, v44
	s_waitcnt lgkmcnt(0)
	s_barrier
	s_and_saveexec_b64 s[10:11], s[34:35]
	s_xor_b64 s[10:11], exec, s[10:11]
	s_and_b64 s[6:7], vcc, exec
	s_cselect_b32 s12, 8, 12
	s_lshl_b64 s[6:7], s[48:49], s12
	s_or_saveexec_b64 s[10:11], s[10:11]
	s_or_b32 s61, s0, 16
	v_mov_b32_e32 v2, s12
	v_mov_b64_e32 v[0:1], s[6:7]
	s_xor_b64 exec, exec, s[10:11]
	s_cbranch_execz .LBB0_1096
	s_lshl_b32 s0, -1, s1
	s_not_b32 s0, s0
	s_and_b64 s[6:7], vcc, exec
	s_cselect_b32 s6, 8, 12
	s_lshl_b64 s[12:13], s[48:49], s6
	s_lshl_b64 s[6:7], s[12:13], 1
	s_add_u32 s14, s51, s6
	s_addc_u32 s15, s52, s7
	s_mov_b64 s[16:17], 0
	v_mov_b32_e32 v0, v44
